# DSA select: second histogram pass also 8 key blocks per trip
# baseline (speedup 1.0000x reference)
.Lsel8b_top:
	s_cmp_lt_u32 s43, 8
	s_cbranch_scc1 .LBB0_218
	ds_read_u16 v208, v2
	ds_read_u16 v209, v2 offset:128
	ds_read_u16 v210, v2 offset:256
	ds_read_u16 v211, v2 offset:384
	ds_read_u16 v212, v2 offset:512
	ds_read_u16 v213, v2 offset:640
	ds_read_u16 v214, v2 offset:768
	ds_read_u16 v215, v2 offset:896
	s_waitcnt lgkmcnt(0)
	v_cmp_ge_u32_e32 vcc, s50, v3
	s_and_saveexec_b64 s[28:29], vcc
	v_lshrrev_b32_e32 v217, 8, v208
	v_cmp_eq_u32_e32 vcc, v217, v13
	s_and_b64 exec, exec, vcc
	v_and_b32_e32 v208, 0xff, v208
	v_lshl_add_u32 v208, v208, 2, s38
	ds_add_u32 v208, v196
	s_or_b64 exec, exec, s[28:29]
	v_add_u32_e32 v216, 64, v3
	v_cmp_ge_u32_e32 vcc, s50, v216
	s_and_saveexec_b64 s[28:29], vcc
	v_lshrrev_b32_e32 v217, 8, v209
	v_cmp_eq_u32_e32 vcc, v217, v13
	s_and_b64 exec, exec, vcc
	v_and_b32_e32 v209, 0xff, v209
	v_lshl_add_u32 v209, v209, 2, s38
	ds_add_u32 v209, v196
	s_or_b64 exec, exec, s[28:29]
	v_add_u32_e32 v216, 128, v3
	v_cmp_ge_u32_e32 vcc, s50, v216
	s_and_saveexec_b64 s[28:29], vcc
	v_lshrrev_b32_e32 v217, 8, v210
	v_cmp_eq_u32_e32 vcc, v217, v13
	s_and_b64 exec, exec, vcc
	v_and_b32_e32 v210, 0xff, v210
	v_lshl_add_u32 v210, v210, 2, s38
	ds_add_u32 v210, v196
	s_or_b64 exec, exec, s[28:29]
	v_add_u32_e32 v216, 192, v3
	v_cmp_ge_u32_e32 vcc, s50, v216
	s_and_saveexec_b64 s[28:29], vcc
	v_lshrrev_b32_e32 v217, 8, v211
	v_cmp_eq_u32_e32 vcc, v217, v13
	s_and_b64 exec, exec, vcc
	v_and_b32_e32 v211, 0xff, v211
	v_lshl_add_u32 v211, v211, 2, s38
	ds_add_u32 v211, v196
	s_or_b64 exec, exec, s[28:29]
	v_add_u32_e32 v216, 256, v3
	v_cmp_ge_u32_e32 vcc, s50, v216
	s_and_saveexec_b64 s[28:29], vcc
	v_lshrrev_b32_e32 v217, 8, v212
	v_cmp_eq_u32_e32 vcc, v217, v13
	s_and_b64 exec, exec, vcc
	v_and_b32_e32 v212, 0xff, v212
	v_lshl_add_u32 v212, v212, 2, s38
	ds_add_u32 v212, v196
	s_or_b64 exec, exec, s[28:29]
	v_add_u32_e32 v216, 320, v3
	v_cmp_ge_u32_e32 vcc, s50, v216
	s_and_saveexec_b64 s[28:29], vcc
	v_lshrrev_b32_e32 v217, 8, v213
	v_cmp_eq_u32_e32 vcc, v217, v13
	s_and_b64 exec, exec, vcc
	v_and_b32_e32 v213, 0xff, v213
	v_lshl_add_u32 v213, v213, 2, s38
	ds_add_u32 v213, v196
	s_or_b64 exec, exec, s[28:29]
	v_add_u32_e32 v216, 384, v3
	v_cmp_ge_u32_e32 vcc, s50, v216
	s_and_saveexec_b64 s[28:29], vcc
	v_lshrrev_b32_e32 v217, 8, v214
	v_cmp_eq_u32_e32 vcc, v217, v13
	s_and_b64 exec, exec, vcc
	v_and_b32_e32 v214, 0xff, v214
	v_lshl_add_u32 v214, v214, 2, s38
	ds_add_u32 v214, v196
	s_or_b64 exec, exec, s[28:29]
	v_add_u32_e32 v216, 448, v3
	v_cmp_ge_u32_e32 vcc, s50, v216
	s_and_saveexec_b64 s[28:29], vcc
	v_lshrrev_b32_e32 v217, 8, v215
	v_cmp_eq_u32_e32 vcc, v217, v13
	s_and_b64 exec, exec, vcc
	v_and_b32_e32 v215, 0xff, v215
	v_lshl_add_u32 v215, v215, 2, s38
	ds_add_u32 v215, v196
	s_or_b64 exec, exec, s[28:29]
	s_add_i32 s43, s43, -8
	v_add_u32_e32 v2, 0x400, v2
	v_add_u32_e32 v3, 0x200, v3
	s_cmp_eq_u32 s43, 0
	s_cbranch_scc1 .LBB0_224
	s_branch .Lsel8b_top
